# v26 plus: waves 4-7 run finishSM before QK inside each attention half-step (complementary block order per SIMD pair)
# speedup vs baseline: 1.0070x; 1.0070x over previous
.LBB0_551:
	s_add_i32 s9, s29, 0xffffff80
	s_cmp_gt_i32 s9, s59
	s_cselect_b64 s[0:1], -1, 0
	s_add_i32 s78, s29, 0xffffffbf
	s_cmp_le_i32 s78, s60
	s_cselect_b64 s[40:41], -1, 0
	s_or_b64 s[0:1], s[0:1], s[40:41]
	s_and_b64 vcc, exec, s[0:1]
	v_add_u32_e32 v197, s29, v234
	v_readfirstlane_b32 s40, v252
	s_nop 0
	s_cmpk_ge_u32 s40, 0x100
	s_cbranch_scc1 .Lst1_b
	s_cbranch_vccnz .LBB0_553
	v_add_u32_e32 v0, 0xffffff80, v197
	v_cvt_f32_i32_e32 v0, v0
	ds_read_b128 v[2:5], v235 offset:49152
	v_mov_b32_e32 v205, v204
	v_fma_f32 v117, s61, v0, s61
	v_add_f32_e32 v118, s61, v117
	v_mul_f32_e32 v116, s61, v0
	v_add_f32_e32 v119, s61, v118
	v_pk_add_f32 v[120:121], v[206:207], v[116:117]
	v_pk_add_f32 v[122:123], v[206:207], v[118:119]
	v_pk_add_f32 v[124:125], v[206:207], v[120:121]
	v_pk_add_f32 v[126:127], v[206:207], v[122:123]
	s_waitcnt vmcnt(0)
	v_pk_add_f32 v[128:129], v[206:207], v[124:125]
	v_pk_add_f32 v[130:131], v[206:207], v[126:127]
	v_pk_add_f32 v[100:101], v[14:15], v[116:117]
	v_pk_add_f32 v[104:105], v[204:205], v[120:121]
	v_pk_add_f32 v[108:109], v[204:205], v[124:125]
	v_pk_add_f32 v[102:103], v[204:205], v[118:119]
	v_pk_add_f32 v[112:113], v[204:205], v[128:129]
	v_pk_add_f32 v[106:107], v[204:205], v[122:123]
	v_pk_add_f32 v[110:111], v[204:205], v[126:127]
	v_pk_add_f32 v[114:115], v[204:205], v[130:131]
	s_waitcnt lgkmcnt(0)
	v_mfma_f32_32x32x16_bf16 v[116:131], v[2:5], v[188:191], v[116:131]
	ds_read_b128 v[2:5], v235 offset:57344
	s_waitcnt lgkmcnt(0)
	v_mfma_f32_32x32x16_bf16 v[100:115], v[2:5], v[188:191], v[100:115]
	ds_read_b128 v[2:5], v236 offset:49152
	s_waitcnt lgkmcnt(0)
	v_mfma_f32_32x32x16_bf16 v[116:131], v[2:5], v[184:187], v[116:131]
	ds_read_b128 v[2:5], v236 offset:57344
	s_waitcnt lgkmcnt(0)
	v_mfma_f32_32x32x16_bf16 v[100:115], v[2:5], v[184:187], v[100:115]
	ds_read_b128 v[2:5], v237 offset:49152
	s_waitcnt lgkmcnt(0)
	v_mfma_f32_32x32x16_bf16 v[116:131], v[2:5], v[180:183], v[116:131]
	ds_read_b128 v[2:5], v237 offset:57344
	s_waitcnt lgkmcnt(0)
	v_mfma_f32_32x32x16_bf16 v[100:115], v[2:5], v[180:183], v[100:115]
	ds_read_b128 v[2:5], v238 offset:49152
	s_waitcnt lgkmcnt(0)
	v_mfma_f32_32x32x16_bf16 v[116:131], v[2:5], v[176:179], v[116:131]
	ds_read_b128 v[2:5], v238 offset:57344
	s_waitcnt lgkmcnt(0)
	v_mfma_f32_32x32x16_bf16 v[100:115], v[2:5], v[176:179], v[100:115]
	ds_read_b128 v[2:5], v235 offset:49280
	s_waitcnt lgkmcnt(0)
	v_mfma_f32_32x32x16_bf16 v[116:131], v[2:5], v[172:175], v[116:131]
	ds_read_b128 v[2:5], v235 offset:57472
	s_waitcnt lgkmcnt(0)
	v_mfma_f32_32x32x16_bf16 v[100:115], v[2:5], v[172:175], v[100:115]
	ds_read_b128 v[2:5], v236 offset:49280
	s_waitcnt lgkmcnt(0)
	v_mfma_f32_32x32x16_bf16 v[116:131], v[2:5], v[168:171], v[116:131]
	ds_read_b128 v[2:5], v236 offset:57472
	s_waitcnt lgkmcnt(0)
	v_mfma_f32_32x32x16_bf16 v[100:115], v[2:5], v[168:171], v[100:115]
	ds_read_b128 v[2:5], v237 offset:49280
	s_waitcnt lgkmcnt(0)
	v_mfma_f32_32x32x16_bf16 v[116:131], v[2:5], v[164:167], v[116:131]
	ds_read_b128 v[2:5], v237 offset:57472
	s_waitcnt lgkmcnt(0)
	v_mfma_f32_32x32x16_bf16 v[100:115], v[2:5], v[164:167], v[100:115]
	ds_read_b128 v[2:5], v238 offset:49280
	s_waitcnt lgkmcnt(0)
	v_mfma_f32_32x32x16_bf16 v[116:131], v[2:5], v[160:163], v[116:131]
	ds_read_b128 v[2:5], v238 offset:57472
	s_waitcnt lgkmcnt(0)
	v_mfma_f32_32x32x16_bf16 v[100:115], v[2:5], v[160:163], v[100:115]
	s_branch .LBB0_554
.Lst1_b:
	v_add_f32_e32 v0, 0, v193
	v_add_f32_e32 v0, v195, v0
	v_add_f32_e32 v0, v159, v0
	v_add_f32_e32 v0, v194, v0
	v_add_f32_e32 v0, v157, v0
	v_add_f32_e32 v0, v192, v0
	v_add_f32_e32 v0, v156, v0
	v_add_f32_e32 v0, v158, v0
	v_add_f32_e32 v0, v150, v0
	v_add_f32_e32 v0, v153, v0
	v_add_f32_e32 v0, v149, v0
	v_add_f32_e32 v0, v151, v0
	v_exp_f32_e32 v2, v146
	v_add_f32_e32 v0, v148, v0
	v_exp_f32_e32 v3, v147
	v_add_f32_e32 v0, v155, v0
	v_exp_f32_e32 v4, v144
	v_add_f32_e32 v0, v152, v0
	v_exp_f32_e32 v5, v145
	v_add_f32_e32 v0, v154, v0
	v_exp_f32_e32 v6, v132
	v_add_f32_e32 v0, v2, v0
	v_exp_f32_e32 v7, v133
	v_add_f32_e32 v0, v3, v0
	v_exp_f32_e32 v8, v134
	v_add_f32_e32 v0, v4, v0
	v_exp_f32_e32 v9, v135
	v_add_f32_e32 v0, v5, v0
	v_exp_f32_e32 v10, v136
	v_add_f32_e32 v0, v6, v0
	v_exp_f32_e32 v11, v137
	v_add_f32_e32 v0, v7, v0
	v_exp_f32_e32 v12, v138
	v_add_f32_e32 v0, v8, v0
	v_exp_f32_e32 v13, v139
	v_add_f32_e32 v0, v9, v0
	v_exp_f32_e32 v17, v140
	v_add_f32_e32 v0, v10, v0
	v_exp_f32_e32 v30, v141
	v_add_f32_e32 v0, v11, v0
	v_exp_f32_e32 v31, v142
	v_add_f32_e32 v0, v12, v0
	v_exp_f32_e32 v99, v143
	v_add_f32_e32 v0, v13, v0
	v_add_f32_e32 v0, v17, v0
	v_add_f32_e32 v0, v30, v0
	v_add_f32_e32 v0, v31, v0
	v_add_f32_e32 v0, v99, v0
	v_mov_b32_e32 v239, v0
	v_cvt_pk_bf16_f32 v18, v193, v195
	v_cvt_pk_bf16_f32 v19, v159, v194
	v_cvt_pk_bf16_f32 v20, v157, v192
	v_cvt_pk_bf16_f32 v21, v156, v158
	v_cvt_pk_bf16_f32 v22, v150, v153
	v_cvt_pk_bf16_f32 v23, v149, v151
	v_cvt_pk_bf16_f32 v24, v148, v155
	v_cvt_pk_bf16_f32 v25, v152, v154
	v_cvt_pk_bf16_f32 v26, v2, v3
	v_cvt_pk_bf16_f32 v27, v4, v5
	v_cvt_pk_bf16_f32 v28, v6, v7
	v_cvt_pk_bf16_f32 v29, v8, v9
	v_cvt_pk_bf16_f32 v96, v10, v11
	v_cvt_pk_bf16_f32 v97, v12, v13
	v_cvt_pk_bf16_f32 v98, v17, v30
	v_cvt_pk_bf16_f32 v99, v31, v99
	s_nop 1
	v_permlane32_swap_b32_e32 v0, v239
	v_permlane32_swap_b32_e32 v18, v20
	v_permlane32_swap_b32_e32 v19, v21
	v_permlane32_swap_b32_e32 v22, v24
	v_permlane32_swap_b32_e32 v23, v25
	v_permlane32_swap_b32_e32 v26, v28
	v_permlane32_swap_b32_e32 v27, v29
	v_permlane32_swap_b32_e32 v96, v98
	v_permlane32_swap_b32_e32 v97, v99
	s_and_b64 vcc, exec, s[0:1]
	s_cbranch_vccnz .Lst1_b_inact
	v_add_u32_e32 v240, 0xffffff80, v197
	v_cvt_f32_i32_e32 v240, v240
	ds_read_b128 v[2:5], v235 offset:49152
	v_mov_b32_e32 v205, v204
	v_fma_f32 v117, s61, v240, s61
	v_add_f32_e32 v118, s61, v117
	v_mul_f32_e32 v116, s61, v240
	v_add_f32_e32 v119, s61, v118
	v_pk_add_f32 v[120:121], v[206:207], v[116:117]
	v_pk_add_f32 v[122:123], v[206:207], v[118:119]
	v_pk_add_f32 v[124:125], v[206:207], v[120:121]
	v_pk_add_f32 v[126:127], v[206:207], v[122:123]
	s_waitcnt vmcnt(0)
	v_pk_add_f32 v[128:129], v[206:207], v[124:125]
	v_pk_add_f32 v[130:131], v[206:207], v[126:127]
	v_pk_add_f32 v[100:101], v[14:15], v[116:117]
	v_pk_add_f32 v[104:105], v[204:205], v[120:121]
	v_pk_add_f32 v[108:109], v[204:205], v[124:125]
	v_pk_add_f32 v[102:103], v[204:205], v[118:119]
	v_pk_add_f32 v[112:113], v[204:205], v[128:129]
	v_pk_add_f32 v[106:107], v[204:205], v[122:123]
	v_pk_add_f32 v[110:111], v[204:205], v[126:127]
	v_pk_add_f32 v[114:115], v[204:205], v[130:131]
	s_waitcnt lgkmcnt(0)
	v_mfma_f32_32x32x16_bf16 v[116:131], v[2:5], v[188:191], v[116:131]
	ds_read_b128 v[2:5], v235 offset:57344
	s_waitcnt lgkmcnt(0)
	v_mfma_f32_32x32x16_bf16 v[100:115], v[2:5], v[188:191], v[100:115]
	ds_read_b128 v[2:5], v236 offset:49152
	s_waitcnt lgkmcnt(0)
	v_mfma_f32_32x32x16_bf16 v[116:131], v[2:5], v[184:187], v[116:131]
	ds_read_b128 v[2:5], v236 offset:57344
	s_waitcnt lgkmcnt(0)
	v_mfma_f32_32x32x16_bf16 v[100:115], v[2:5], v[184:187], v[100:115]
	ds_read_b128 v[2:5], v237 offset:49152
	s_waitcnt lgkmcnt(0)
	v_mfma_f32_32x32x16_bf16 v[116:131], v[2:5], v[180:183], v[116:131]
	ds_read_b128 v[2:5], v237 offset:57344
	s_waitcnt lgkmcnt(0)
	v_mfma_f32_32x32x16_bf16 v[100:115], v[2:5], v[180:183], v[100:115]
	ds_read_b128 v[2:5], v238 offset:49152
	s_waitcnt lgkmcnt(0)
	v_mfma_f32_32x32x16_bf16 v[116:131], v[2:5], v[176:179], v[116:131]
	ds_read_b128 v[2:5], v238 offset:57344
	s_waitcnt lgkmcnt(0)
	v_mfma_f32_32x32x16_bf16 v[100:115], v[2:5], v[176:179], v[100:115]
	ds_read_b128 v[2:5], v235 offset:49280
	s_waitcnt lgkmcnt(0)
	v_mfma_f32_32x32x16_bf16 v[116:131], v[2:5], v[172:175], v[116:131]
	ds_read_b128 v[2:5], v235 offset:57472
	s_waitcnt lgkmcnt(0)
	v_mfma_f32_32x32x16_bf16 v[100:115], v[2:5], v[172:175], v[100:115]
	ds_read_b128 v[2:5], v236 offset:49280
	s_waitcnt lgkmcnt(0)
	v_mfma_f32_32x32x16_bf16 v[116:131], v[2:5], v[168:171], v[116:131]
	ds_read_b128 v[2:5], v236 offset:57472
	s_waitcnt lgkmcnt(0)
	v_mfma_f32_32x32x16_bf16 v[100:115], v[2:5], v[168:171], v[100:115]
	ds_read_b128 v[2:5], v237 offset:49280
	s_waitcnt lgkmcnt(0)
	v_mfma_f32_32x32x16_bf16 v[116:131], v[2:5], v[164:167], v[116:131]
	ds_read_b128 v[2:5], v237 offset:57472
	s_waitcnt lgkmcnt(0)
	v_mfma_f32_32x32x16_bf16 v[100:115], v[2:5], v[164:167], v[100:115]
	ds_read_b128 v[2:5], v238 offset:49280
	s_waitcnt lgkmcnt(0)
	v_mfma_f32_32x32x16_bf16 v[116:131], v[2:5], v[160:163], v[116:131]
	ds_read_b128 v[2:5], v238 offset:57472
	s_waitcnt lgkmcnt(0)
	v_mfma_f32_32x32x16_bf16 v[100:115], v[2:5], v[160:163], v[100:115]
	s_branch .Lst1_join
.Lst1_b_inact:
	s_waitcnt vmcnt(0)
	v_mov_b32_e32 v100, v16
	v_mov_b32_e32 v101, v16
	v_mov_b32_e32 v102, v16
	v_mov_b32_e32 v103, v16
	v_mov_b32_e32 v104, v16
	v_mov_b32_e32 v105, v16
	v_mov_b32_e32 v106, v16
	v_mov_b32_e32 v107, v16
	v_mov_b32_e32 v108, v16
	v_mov_b32_e32 v109, v16
	v_mov_b32_e32 v110, v16
	v_mov_b32_e32 v111, v16
	v_mov_b32_e32 v112, v16
	v_mov_b32_e32 v113, v16
	v_mov_b32_e32 v114, v16
	v_mov_b32_e32 v115, v16
	v_mov_b32_e32 v116, v16
	v_mov_b32_e32 v117, v16
	v_mov_b32_e32 v118, v16
	v_mov_b32_e32 v119, v16
	v_mov_b32_e32 v120, v16
	v_mov_b32_e32 v121, v16
	v_mov_b32_e32 v122, v16
	v_mov_b32_e32 v123, v16
	v_mov_b32_e32 v124, v16
	v_mov_b32_e32 v125, v16
	v_mov_b32_e32 v126, v16
	v_mov_b32_e32 v127, v16
	v_mov_b32_e32 v128, v16
	v_mov_b32_e32 v129, v16
	v_mov_b32_e32 v130, v16
	v_mov_b32_e32 v131, v16
	s_branch .Lst1_join

.Lst1_join:
	s_sub_i32 s8, s29, 64
	s_mul_hi_u32 s41, s8, s66
	s_mul_i32 s40, s8, s66
	s_lshl_b64 s[40:41], s[40:41], 1
	s_add_u32 vcc_lo, s76, s40
	s_addc_u32 vcc_hi, s77, s41
	s_add_u32 s40, s22, s40
	s_addc_u32 s41, s23, s41
	v_lshl_add_u64 v[2:3], vcc, 0, v[208:209]
	v_lshl_add_u64 v[6:7], vcc, 0, v[210:211]
	v_lshl_add_u64 v[10:11], s[40:41], 0, v[208:209]
	global_load_dwordx4 v[2:5], v[2:3], off
	s_nop 0
	global_load_dwordx4 v[6:9], v[6:7], off
	v_lshl_add_u64 v[30:31], s[40:41], 0, v[210:211]
	global_load_dwordx4 v[10:13], v[10:11], off
	s_nop 0
	global_load_dwordx4 v[192:195], v[30:31], off
	s_add_i32 s10, s29, 0xffffff40
	s_cmp_le_i32 s10, s59
	s_cselect_b64 s[40:41], -1, 0
	s_add_i32 s10, s29, 0xffffff7f
	s_cmp_gt_i32 s10, s60
	s_cselect_b64 vcc, -1, 0
	s_and_b64 s[40:41], s[40:41], vcc
	s_andn2_b64 vcc, exec, s[40:41]
	s_cbranch_vccnz .LBB0_556
	ds_read_b64_tr_b16 v[132:133], v224 offset:0
	ds_read_b64_tr_b16 v[134:135], v224 offset:0x800
	ds_read_b64_tr_b16 v[136:137], v224 offset:0x1000
	ds_read_b64_tr_b16 v[138:139], v224 offset:0x1800
	ds_read_b64_tr_b16 v[140:141], v224 offset:0x2000
	ds_read_b64_tr_b16 v[142:143], v224 offset:0x2800
	ds_read_b64_tr_b16 v[144:145], v224 offset:0x3000
	ds_read_b64_tr_b16 v[146:147], v224 offset:0x3800
	s_waitcnt lgkmcnt(0)
	s_nop 0
	v_mfma_f32_32x32x16_bf16 v[80:95], v[18:21], v[132:135], v[80:95]
	ds_read_b64_tr_b16 v[132:133], v224 offset:0x200
	ds_read_b64_tr_b16 v[134:135], v224 offset:0xa00
	v_mfma_f32_32x32x16_bf16 v[80:95], v[22:25], v[136:139], v[80:95]
	ds_read_b64_tr_b16 v[136:137], v224 offset:0x1200
	ds_read_b64_tr_b16 v[138:139], v224 offset:0x1a00
	v_mfma_f32_32x32x16_bf16 v[80:95], v[26:29], v[140:143], v[80:95]
	ds_read_b64_tr_b16 v[140:141], v224 offset:0x2200
	ds_read_b64_tr_b16 v[142:143], v224 offset:0x2a00
	v_mfma_f32_32x32x16_bf16 v[80:95], v[96:99], v[144:147], v[80:95]
	ds_read_b64_tr_b16 v[144:145], v224 offset:0x3200
	ds_read_b64_tr_b16 v[146:147], v224 offset:0x3a00
	s_waitcnt lgkmcnt(0)
	v_mfma_f32_32x32x16_bf16 v[64:79], v[18:21], v[132:135], v[64:79]
	ds_read_b64_tr_b16 v[132:133], v224 offset:0x400
	ds_read_b64_tr_b16 v[134:135], v224 offset:0xc00
	v_mfma_f32_32x32x16_bf16 v[64:79], v[22:25], v[136:139], v[64:79]
	ds_read_b64_tr_b16 v[136:137], v224 offset:0x1400
	ds_read_b64_tr_b16 v[138:139], v224 offset:0x1c00
	v_mfma_f32_32x32x16_bf16 v[64:79], v[26:29], v[140:143], v[64:79]
	ds_read_b64_tr_b16 v[140:141], v224 offset:0x2400
	ds_read_b64_tr_b16 v[142:143], v224 offset:0x2c00
	v_mfma_f32_32x32x16_bf16 v[64:79], v[96:99], v[144:147], v[64:79]
	ds_read_b64_tr_b16 v[144:145], v224 offset:0x3400
	ds_read_b64_tr_b16 v[146:147], v224 offset:0x3c00
	s_waitcnt lgkmcnt(0)
	v_mfma_f32_32x32x16_bf16 v[48:63], v[18:21], v[132:135], v[48:63]
	ds_read_b64_tr_b16 v[132:133], v224 offset:0x600
	ds_read_b64_tr_b16 v[134:135], v224 offset:0xe00
	v_mfma_f32_32x32x16_bf16 v[48:63], v[22:25], v[136:139], v[48:63]
	ds_read_b64_tr_b16 v[136:137], v224 offset:0x1600
	ds_read_b64_tr_b16 v[138:139], v224 offset:0x1e00
	v_mfma_f32_32x32x16_bf16 v[48:63], v[26:29], v[140:143], v[48:63]
	ds_read_b64_tr_b16 v[140:141], v224 offset:0x2600
	ds_read_b64_tr_b16 v[142:143], v224 offset:0x2e00
	v_mfma_f32_32x32x16_bf16 v[48:63], v[96:99], v[144:147], v[48:63]
	ds_read_b64_tr_b16 v[144:145], v224 offset:0x3600
	ds_read_b64_tr_b16 v[146:147], v224 offset:0x3e00
	s_waitcnt lgkmcnt(0)
	v_mfma_f32_32x32x16_bf16 v[32:47], v[18:21], v[132:135], v[32:47]
	v_mfma_f32_32x32x16_bf16 v[32:47], v[22:25], v[136:139], v[32:47]
	v_mfma_f32_32x32x16_bf16 v[32:47], v[26:29], v[140:143], v[32:47]
	v_mfma_f32_32x32x16_bf16 v[32:47], v[96:99], v[144:147], v[32:47]

.LBB0_563:
	v_cndmask_b32_e64 v241, v17, v196, s[0:1]
	v_mul_f32_e32 v196, 0xbe0293ee, v241
	v_fmamk_f32 v17, v116, 0x3e0293ee, v196
	v_fmamk_f32 v18, v117, 0x3e0293ee, v196
	v_fmamk_f32 v19, v118, 0x3e0293ee, v196
	v_fmamk_f32 v20, v119, 0x3e0293ee, v196
	v_fmamk_f32 v21, v120, 0x3e0293ee, v196
	v_fmamk_f32 v22, v121, 0x3e0293ee, v196
	v_fmamk_f32 v23, v122, 0x3e0293ee, v196
	v_fmamk_f32 v24, v123, 0x3e0293ee, v196
	v_fmamk_f32 v25, v124, 0x3e0293ee, v196
	v_fmamk_f32 v26, v125, 0x3e0293ee, v196
	v_fmamk_f32 v27, v126, 0x3e0293ee, v196
	v_fmamk_f32 v28, v127, 0x3e0293ee, v196
	v_fmamk_f32 v29, v128, 0x3e0293ee, v196
	v_fmamk_f32 v30, v129, 0x3e0293ee, v196
	v_fmamk_f32 v31, v130, 0x3e0293ee, v196
	v_fmamk_f32 v128, v131, 0x3e0293ee, v196
	v_fmamk_f32 v116, v100, 0x3e0293ee, v196
	v_fmamk_f32 v117, v101, 0x3e0293ee, v196
	v_fmamk_f32 v118, v102, 0x3e0293ee, v196
	v_fmamk_f32 v119, v103, 0x3e0293ee, v196
	v_fmamk_f32 v120, v104, 0x3e0293ee, v196
	v_fmamk_f32 v121, v105, 0x3e0293ee, v196
	v_fmamk_f32 v122, v106, 0x3e0293ee, v196
	v_fmamk_f32 v123, v107, 0x3e0293ee, v196
	v_fmamk_f32 v124, v108, 0x3e0293ee, v196
	v_fmamk_f32 v125, v109, 0x3e0293ee, v196
	v_fmamk_f32 v126, v110, 0x3e0293ee, v196
	v_fmamk_f32 v127, v111, 0x3e0293ee, v196
	v_exp_f32_e32 v96, v17
	v_exp_f32_e32 v97, v18
	v_exp_f32_e32 v98, v19
	v_exp_f32_e32 v99, v20
	v_exp_f32_e32 v100, v21
	v_exp_f32_e32 v101, v22
	v_exp_f32_e32 v102, v23
	v_exp_f32_e32 v103, v24
	v_exp_f32_e32 v104, v25
	v_exp_f32_e32 v105, v26
	v_exp_f32_e32 v106, v27
	v_exp_f32_e32 v107, v28
	v_exp_f32_e32 v108, v29
	v_exp_f32_e32 v109, v30
	v_exp_f32_e32 v110, v31
	v_exp_f32_e32 v111, v128
	v_fmamk_f32 v198, v112, 0x3e0293ee, v196
	v_fmamk_f32 v199, v113, 0x3e0293ee, v196
	v_fmamk_f32 v242, v114, 0x3e0293ee, v196
	v_fmac_f32_e32 v196, 0x3e0293ee, v115
	s_waitcnt lgkmcnt(0)
	s_barrier
	s_cmp_gt_i32 s8, s59
	s_cselect_b64 s[0:1], -1, 0
	s_add_i32 s9, s29, -1
	s_cmp_le_i32 s9, s60
	s_cselect_b64 s[78:79], -1, 0
	s_or_b64 s[0:1], s[0:1], s[78:79]
	s_and_b64 vcc, exec, s[0:1]
	v_readfirstlane_b32 s78, v252
	s_nop 0
	s_cmpk_ge_u32 s78, 0x100
	s_cbranch_scc1 .Lst2_b
	s_cbranch_vccnz .LBB0_565
	v_subrev_u32_e32 v17, 64, v197
	v_cvt_f32_i32_e32 v17, v17
	ds_read_b128 v[18:21], v235 offset:32768
	v_mov_b32_e32 v205, v204
	v_fma_f32 v145, s61, v17, s61
	v_add_f32_e32 v146, s61, v145
	v_mul_f32_e32 v144, s61, v17
	v_add_f32_e32 v147, s61, v146
	v_pk_add_f32 v[148:149], v[206:207], v[144:145]
	v_pk_add_f32 v[150:151], v[206:207], v[146:147]
	v_pk_add_f32 v[152:153], v[206:207], v[148:149]
	v_pk_add_f32 v[154:155], v[206:207], v[150:151]
	v_pk_add_f32 v[156:157], v[206:207], v[152:153]
	v_pk_add_f32 v[158:159], v[206:207], v[154:155]
	v_pk_add_f32 v[128:129], v[14:15], v[144:145]
	v_pk_add_f32 v[132:133], v[204:205], v[148:149]
	v_pk_add_f32 v[136:137], v[204:205], v[152:153]
	v_pk_add_f32 v[130:131], v[204:205], v[146:147]
	v_pk_add_f32 v[140:141], v[204:205], v[156:157]
	v_pk_add_f32 v[134:135], v[204:205], v[150:151]
	v_pk_add_f32 v[138:139], v[204:205], v[154:155]
	v_pk_add_f32 v[142:143], v[204:205], v[158:159]
	s_waitcnt lgkmcnt(0)
	v_mfma_f32_32x32x16_bf16 v[144:159], v[18:21], v[188:191], v[144:159]
	ds_read_b128 v[18:21], v235 offset:40960
	s_waitcnt lgkmcnt(0)
	v_mfma_f32_32x32x16_bf16 v[128:143], v[18:21], v[188:191], v[128:143]
	ds_read_b128 v[18:21], v236 offset:32768
	s_waitcnt lgkmcnt(0)
	v_mfma_f32_32x32x16_bf16 v[144:159], v[18:21], v[184:187], v[144:159]
	ds_read_b128 v[18:21], v236 offset:40960
	s_waitcnt lgkmcnt(0)
	v_mfma_f32_32x32x16_bf16 v[128:143], v[18:21], v[184:187], v[128:143]
	ds_read_b128 v[18:21], v237 offset:32768
	s_waitcnt lgkmcnt(0)
	v_mfma_f32_32x32x16_bf16 v[144:159], v[18:21], v[180:183], v[144:159]
	ds_read_b128 v[18:21], v237 offset:40960
	s_waitcnt lgkmcnt(0)
	v_mfma_f32_32x32x16_bf16 v[128:143], v[18:21], v[180:183], v[128:143]
	ds_read_b128 v[18:21], v238 offset:32768
	s_waitcnt lgkmcnt(0)
	v_mfma_f32_32x32x16_bf16 v[144:159], v[18:21], v[176:179], v[144:159]
	ds_read_b128 v[18:21], v238 offset:40960
	s_waitcnt lgkmcnt(0)
	v_mfma_f32_32x32x16_bf16 v[128:143], v[18:21], v[176:179], v[128:143]
	ds_read_b128 v[18:21], v235 offset:32896
	s_waitcnt lgkmcnt(0)
	v_mfma_f32_32x32x16_bf16 v[144:159], v[18:21], v[172:175], v[144:159]
	ds_read_b128 v[18:21], v235 offset:41088
	s_waitcnt lgkmcnt(0)
	v_mfma_f32_32x32x16_bf16 v[128:143], v[18:21], v[172:175], v[128:143]
	ds_read_b128 v[18:21], v236 offset:32896
	s_waitcnt lgkmcnt(0)
	v_mfma_f32_32x32x16_bf16 v[144:159], v[18:21], v[168:171], v[144:159]
	ds_read_b128 v[18:21], v236 offset:41088
	s_waitcnt lgkmcnt(0)
	v_mfma_f32_32x32x16_bf16 v[128:143], v[18:21], v[168:171], v[128:143]
	ds_read_b128 v[18:21], v237 offset:32896
	s_waitcnt lgkmcnt(0)
	v_mfma_f32_32x32x16_bf16 v[144:159], v[18:21], v[164:167], v[144:159]
	ds_read_b128 v[18:21], v237 offset:41088
	s_waitcnt lgkmcnt(0)
	v_mfma_f32_32x32x16_bf16 v[128:143], v[18:21], v[164:167], v[128:143]
	ds_read_b128 v[18:21], v238 offset:32896
	s_waitcnt lgkmcnt(0)
	v_mfma_f32_32x32x16_bf16 v[144:159], v[18:21], v[160:163], v[144:159]
	ds_read_b128 v[18:21], v238 offset:41088
	s_waitcnt lgkmcnt(0)
	v_mfma_f32_32x32x16_bf16 v[128:143], v[18:21], v[160:163], v[128:143]
	s_branch .LBB0_566
.Lst2_b:
	v_subrev_u32_e32 v243, 64, v197
	v_cvt_f32_i32_e32 v243, v243
	v_add_f32_e32 v17, 0, v96
	v_add_f32_e32 v17, v97, v17
	v_add_f32_e32 v17, v98, v17
	v_add_f32_e32 v17, v99, v17
	v_add_f32_e32 v17, v100, v17
	v_add_f32_e32 v17, v101, v17
	v_add_f32_e32 v17, v102, v17
	v_add_f32_e32 v17, v103, v17
	v_add_f32_e32 v17, v104, v17
	v_add_f32_e32 v17, v105, v17
	v_add_f32_e32 v17, v106, v17
	v_add_f32_e32 v17, v107, v17
	v_exp_f32_e32 v112, v116
	v_add_f32_e32 v17, v108, v17
	v_exp_f32_e32 v113, v117
	v_add_f32_e32 v17, v109, v17
	v_exp_f32_e32 v114, v118
	v_add_f32_e32 v17, v110, v17
	v_exp_f32_e32 v115, v119
	v_add_f32_e32 v17, v111, v17
	v_exp_f32_e32 v116, v120
	v_add_f32_e32 v17, v112, v17
	v_exp_f32_e32 v117, v121
	v_add_f32_e32 v17, v113, v17
	v_exp_f32_e32 v118, v122
	v_add_f32_e32 v17, v114, v17
	v_exp_f32_e32 v119, v123
	v_add_f32_e32 v17, v115, v17
	v_exp_f32_e32 v120, v124
	v_add_f32_e32 v17, v116, v17
	v_exp_f32_e32 v121, v125
	v_add_f32_e32 v17, v117, v17
	v_exp_f32_e32 v122, v126
	v_add_f32_e32 v17, v118, v17
	v_exp_f32_e32 v123, v127
	v_add_f32_e32 v17, v119, v17
	v_exp_f32_e32 v124, v198
	v_add_f32_e32 v17, v120, v17
	v_exp_f32_e32 v125, v199
	v_add_f32_e32 v17, v121, v17
	v_exp_f32_e32 v126, v242
	v_add_f32_e32 v17, v122, v17
	v_exp_f32_e32 v127, v196
	v_add_f32_e32 v17, v123, v17
	v_add_f32_e32 v17, v124, v17
	v_add_f32_e32 v17, v125, v17
	v_add_f32_e32 v17, v126, v17
	v_add_f32_e32 v17, v127, v17
	v_mov_b32_e32 v30, v17
	v_cvt_pk_bf16_f32 v18, v96, v97
	v_cvt_pk_bf16_f32 v19, v98, v99
	v_cvt_pk_bf16_f32 v20, v100, v101
	v_cvt_pk_bf16_f32 v21, v102, v103
	v_cvt_pk_bf16_f32 v22, v104, v105
	v_cvt_pk_bf16_f32 v23, v106, v107
	v_cvt_pk_bf16_f32 v24, v108, v109
	v_cvt_pk_bf16_f32 v25, v110, v111
	v_cvt_pk_bf16_f32 v26, v112, v113
	v_cvt_pk_bf16_f32 v27, v114, v115
	v_cvt_pk_bf16_f32 v28, v116, v117
	v_cvt_pk_bf16_f32 v29, v118, v119
	v_cvt_pk_bf16_f32 v196, v120, v121
	v_cvt_pk_bf16_f32 v197, v122, v123
	v_cvt_pk_bf16_f32 v198, v124, v125
	v_cvt_pk_bf16_f32 v199, v126, v127
	s_nop 1
	v_permlane32_swap_b32_e32 v17, v30
	v_permlane32_swap_b32_e32 v18, v20
	v_permlane32_swap_b32_e32 v19, v21
	v_permlane32_swap_b32_e32 v22, v24
	v_permlane32_swap_b32_e32 v23, v25
	v_permlane32_swap_b32_e32 v26, v28
	v_permlane32_swap_b32_e32 v27, v29
	v_permlane32_swap_b32_e32 v196, v198
	v_permlane32_swap_b32_e32 v197, v199
	s_and_b64 vcc, exec, s[0:1]
	s_cbranch_vccnz .Lst2_b_inact
	ds_read_b128 v[2:5], v235 offset:32768
	v_mov_b32_e32 v205, v204
	v_fma_f32 v145, s61, v243, s61
	v_add_f32_e32 v146, s61, v145
	v_mul_f32_e32 v144, s61, v243
	v_add_f32_e32 v147, s61, v146
	v_pk_add_f32 v[148:149], v[206:207], v[144:145]
	v_pk_add_f32 v[150:151], v[206:207], v[146:147]
	v_pk_add_f32 v[152:153], v[206:207], v[148:149]
	v_pk_add_f32 v[154:155], v[206:207], v[150:151]
	v_pk_add_f32 v[156:157], v[206:207], v[152:153]
	v_pk_add_f32 v[158:159], v[206:207], v[154:155]
	v_pk_add_f32 v[128:129], v[14:15], v[144:145]
	v_pk_add_f32 v[132:133], v[204:205], v[148:149]
	v_pk_add_f32 v[136:137], v[204:205], v[152:153]
	v_pk_add_f32 v[130:131], v[204:205], v[146:147]
	v_pk_add_f32 v[140:141], v[204:205], v[156:157]
	v_pk_add_f32 v[134:135], v[204:205], v[150:151]
	v_pk_add_f32 v[138:139], v[204:205], v[154:155]
	v_pk_add_f32 v[142:143], v[204:205], v[158:159]
	s_waitcnt lgkmcnt(0)
	v_mfma_f32_32x32x16_bf16 v[144:159], v[2:5], v[188:191], v[144:159]
	ds_read_b128 v[2:5], v235 offset:40960
	s_waitcnt lgkmcnt(0)
	v_mfma_f32_32x32x16_bf16 v[128:143], v[2:5], v[188:191], v[128:143]
	ds_read_b128 v[2:5], v236 offset:32768
	s_waitcnt lgkmcnt(0)
	v_mfma_f32_32x32x16_bf16 v[144:159], v[2:5], v[184:187], v[144:159]
	ds_read_b128 v[2:5], v236 offset:40960
	s_waitcnt lgkmcnt(0)
	v_mfma_f32_32x32x16_bf16 v[128:143], v[2:5], v[184:187], v[128:143]
	ds_read_b128 v[2:5], v237 offset:32768
	s_waitcnt lgkmcnt(0)
	v_mfma_f32_32x32x16_bf16 v[144:159], v[2:5], v[180:183], v[144:159]
	ds_read_b128 v[2:5], v237 offset:40960
	s_waitcnt lgkmcnt(0)
	v_mfma_f32_32x32x16_bf16 v[128:143], v[2:5], v[180:183], v[128:143]
	ds_read_b128 v[2:5], v238 offset:32768
	s_waitcnt lgkmcnt(0)
	v_mfma_f32_32x32x16_bf16 v[144:159], v[2:5], v[176:179], v[144:159]
	ds_read_b128 v[2:5], v238 offset:40960
	s_waitcnt lgkmcnt(0)
	v_mfma_f32_32x32x16_bf16 v[128:143], v[2:5], v[176:179], v[128:143]
	ds_read_b128 v[2:5], v235 offset:32896
	s_waitcnt lgkmcnt(0)
	v_mfma_f32_32x32x16_bf16 v[144:159], v[2:5], v[172:175], v[144:159]
	ds_read_b128 v[2:5], v235 offset:41088
	s_waitcnt lgkmcnt(0)
	v_mfma_f32_32x32x16_bf16 v[128:143], v[2:5], v[172:175], v[128:143]
	ds_read_b128 v[2:5], v236 offset:32896
	s_waitcnt lgkmcnt(0)
	v_mfma_f32_32x32x16_bf16 v[144:159], v[2:5], v[168:171], v[144:159]
	ds_read_b128 v[2:5], v236 offset:41088
	s_waitcnt lgkmcnt(0)
	v_mfma_f32_32x32x16_bf16 v[128:143], v[2:5], v[168:171], v[128:143]
	ds_read_b128 v[2:5], v237 offset:32896
	s_waitcnt lgkmcnt(0)
	v_mfma_f32_32x32x16_bf16 v[144:159], v[2:5], v[164:167], v[144:159]
	ds_read_b128 v[2:5], v237 offset:41088
	s_waitcnt lgkmcnt(0)
	v_mfma_f32_32x32x16_bf16 v[128:143], v[2:5], v[164:167], v[128:143]
	ds_read_b128 v[2:5], v238 offset:32896
	s_waitcnt lgkmcnt(0)
	v_mfma_f32_32x32x16_bf16 v[144:159], v[2:5], v[160:163], v[144:159]
	ds_read_b128 v[2:5], v238 offset:41088
	s_waitcnt lgkmcnt(0)
	v_mfma_f32_32x32x16_bf16 v[128:143], v[2:5], v[160:163], v[128:143]
	s_branch .Lst2_join
.Lst2_b_inact:
	s_waitcnt vmcnt(0)
	v_mov_b32_e32 v128, v16
	v_mov_b32_e32 v129, v16
	v_mov_b32_e32 v130, v16
	v_mov_b32_e32 v131, v16
	v_mov_b32_e32 v132, v16
	v_mov_b32_e32 v133, v16
	v_mov_b32_e32 v134, v16
	v_mov_b32_e32 v135, v16
	v_mov_b32_e32 v136, v16
	v_mov_b32_e32 v137, v16
	v_mov_b32_e32 v138, v16
	v_mov_b32_e32 v139, v16
	v_mov_b32_e32 v140, v16
	v_mov_b32_e32 v141, v16
	v_mov_b32_e32 v142, v16
	v_mov_b32_e32 v143, v16
	v_mov_b32_e32 v144, v16
	v_mov_b32_e32 v145, v16
	v_mov_b32_e32 v146, v16
	v_mov_b32_e32 v147, v16
	v_mov_b32_e32 v148, v16
	v_mov_b32_e32 v149, v16
	v_mov_b32_e32 v150, v16
	v_mov_b32_e32 v151, v16
	v_mov_b32_e32 v152, v16
	v_mov_b32_e32 v153, v16
	v_mov_b32_e32 v154, v16
	v_mov_b32_e32 v155, v16
	v_mov_b32_e32 v156, v16
	v_mov_b32_e32 v157, v16
	v_mov_b32_e32 v158, v16
	v_mov_b32_e32 v159, v16
	s_branch .Lst2_join

.Lst2_join:
	s_add_i32 s10, s51, 1
	s_cmp_lt_i32 s10, s62
	s_cselect_b64 s[78:79], -1, 0
	s_cmp_ge_i32 s10, s62
	s_cbranch_scc1 .LBB0_569
	s_mul_hi_u32 vcc_hi, s29, s66
	s_mul_i32 vcc_lo, s29, s66
	s_lshl_b64 vcc, vcc, 1
	s_add_u32 s10, s76, vcc_lo
	s_addc_u32 s11, s77, vcc_hi
	s_add_u32 vcc_lo, s22, vcc_lo
	s_addc_u32 vcc_hi, s23, vcc_hi
	v_lshl_add_u64 v[2:3], s[10:11], 0, v[208:209]
	v_lshl_add_u64 v[6:7], s[10:11], 0, v[210:211]
	v_lshl_add_u64 v[10:11], vcc, 0, v[208:209]
	v_lshl_add_u64 v[192:193], vcc, 0, v[210:211]
	global_load_dwordx4 v[2:5], v[2:3], off
	s_nop 0
	global_load_dwordx4 v[6:9], v[6:7], off
	s_nop 0
	global_load_dwordx4 v[10:13], v[10:11], off
	s_nop 0
	global_load_dwordx4 v[192:195], v[192:193], off
	s_and_b64 vcc, exec, s[40:41]
	s_cbranch_vccz .LBB0_570
